# v18 + z direct stores + pop look-ahead at last key tile + MLA early start (z polled at epilogue) + retention/state packed f32 split, stacked
# baseline (speedup 1.0000x reference)
.LBB0_203:
	v_add_u32_e32 v56, 0, v112
	s_waitcnt vmcnt(0)
	s_mov_b64 s[100:101], exec
	s_mov_b64 exec, s[12:13]
	global_load_dword v184, v[174:175], off sc1
	s_mov_b64 exec, s[42:43]
	global_atomic_add v221, v[182:183], v181, off sc0
	s_mov_b64 exec, s[100:101]
	s_barrier
	v_add_u32_e32 v36, v56, v113
	ds_read_b128 v[32:35], v36 offset:4096
	ds_read_b128 v[48:51], v36
	v_add_u32_e32 v57, v56, v114
	ds_read_b128 v[52:55], v57 offset:4096
	ds_read_b128 v[94:97], v57
	v_add_u32_e32 v58, v56, v111
	s_waitcnt lgkmcnt(3)
	v_mfma_f32_32x32x16_bf16 v[32:47], v[32:35], v[76:79], 0
	v_add_u32_e32 v56, v56, v110
	v_readlane_b32 s0, v255, 2
	v_readlane_b32 s1, v255, 3
	s_andn2_b64 vcc, exec, s[0:1]
	ds_read_b128 v[100:103], v58
	s_waitcnt lgkmcnt(2)
	v_mfma_f32_32x32x16_bf16 v[32:47], v[52:55], v[72:75], v[32:47]
	ds_read_b128 v[52:55], v58 offset:4096
	s_waitcnt lgkmcnt(0)
	v_mfma_f32_32x32x16_bf16 v[32:47], v[52:55], v[68:71], v[32:47]
	ds_read_b128 v[52:55], v56 offset:4096
	ds_read_b128 v[110:113], v56
	s_waitcnt lgkmcnt(1)
	v_mfma_f32_32x32x16_bf16 v[32:47], v[52:55], v[64:67], v[32:47]
	v_add_u32_e32 v52, 0, v108
	v_add3_u32 v106, v52, v109, v106
	ds_read_b64_tr_b16 v[90:91], v106 offset:12288
	ds_read_b64_tr_b16 v[92:93], v106 offset:12800
	ds_read_b64_tr_b16 v[82:83], v106 offset:13312
	ds_read_b64_tr_b16 v[84:85], v106 offset:13824
	v_mfma_f32_32x32x16_bf16 v[48:63], v[48:51], v[76:79], 0
	v_add_u32_e32 v76, 0xc0, v107
	v_cvt_f32_i32_e32 v107, v76
	ds_read_b64_tr_b16 v[86:87], v106 offset:14336
	ds_read_b64_tr_b16 v[88:89], v106 offset:14848
	ds_read_b64_tr_b16 v[76:77], v106 offset:15360
	ds_read_b64_tr_b16 v[78:79], v106 offset:15872
	v_mfma_f32_32x32x16_bf16 v[48:63], v[94:97], v[72:75], v[48:63]
	v_add_f32_e32 v74, 0x41d00000, v107
	v_add_f32_e32 v75, 0x41d80000, v107
	v_add_f32_e32 v72, 0x42000000, v74
	v_add_f32_e32 v73, 0x42000000, v75
	v_fma_f32 v72, v72, v104, v105
	v_fma_f32 v73, v73, v104, v105
	v_exp_f32_e32 v72, v72
	v_mfma_f32_32x32x16_bf16 v[48:63], v[100:103], v[68:71], v[48:63]
	v_exp_f32_e32 v73, v73
	s_nop 0
	v_mul_f32_e32 v68, v46, v72
	v_mul_f32_e32 v69, v47, v73
	v_fma_f32 v46, v74, v104, v105
	v_fma_f32 v47, v75, v104, v105
	s_waitcnt lgkmcnt(8)
	v_mfma_f32_32x32x16_bf16 v[48:63], v[110:113], v[64:67], v[48:63]
	v_exp_f32_e32 v46, v46
	v_exp_f32_e32 v47, v47
	v_add_f32_e32 v65, 0x41c80000, v107
	v_add_f32_e32 v67, 0x41980000, v107
	v_add_f32_e32 v74, 0x41200000, v107
	v_add_f32_e32 v75, 0x41300000, v107
	v_add_f32_e32 v72, 0x42000000, v74
	s_nop 4
	v_mul_f32_e32 v62, v62, v46
	v_mul_f32_e32 v63, v63, v47
	v_add_f32_e32 v46, 0x41c00000, v107
	v_add_f32_e32 v47, 0x42000000, v46
	v_fma_f32 v47, v47, v104, v105
	v_exp_f32_e32 v64, v47
	v_fma_f32 v46, v46, v104, v105
	v_fma_f32 v47, v65, v104, v105
	v_exp_f32_e32 v46, v46
	v_exp_f32_e32 v47, v47
	v_add_f32_e32 v73, 0x42000000, v75
	v_fma_f32 v74, v74, v104, v105
	v_fma_f32 v75, v75, v104, v105
	v_mul_f32_e32 v60, v60, v46
	v_mul_f32_e32 v61, v61, v47
	v_add_f32_e32 v46, 0x41900000, v107
	v_add_f32_e32 v47, 0x42000000, v46
	v_fma_f32 v47, v47, v104, v105
	v_exp_f32_e32 v66, v47
	v_fma_f32 v46, v46, v104, v105
	v_fma_f32 v47, v67, v104, v105
	v_exp_f32_e32 v46, v46
	v_exp_f32_e32 v47, v47
	v_exp_f32_e32 v74, v74
	v_exp_f32_e32 v75, v75
	v_fma_f32 v72, v72, v104, v105
	v_mul_f32_e32 v58, v58, v46
	v_mul_f32_e32 v59, v59, v47
	v_add_f32_e32 v46, 0x41800000, v107
	v_add_f32_e32 v47, 0x42000000, v46
	v_fma_f32 v47, v47, v104, v105
	v_exp_f32_e32 v70, v47
	v_add_f32_e32 v47, 0x41880000, v107
	v_add_f32_e32 v71, 0x42000000, v47
	v_fma_f32 v46, v46, v104, v105
	v_fma_f32 v47, v47, v104, v105
	v_exp_f32_e32 v46, v46
	v_exp_f32_e32 v47, v47
	v_mul_f32_e32 v54, v54, v74
	v_mul_f32_e32 v55, v55, v75
	v_add_f32_e32 v74, 2.0, v107
	v_fma_f32 v73, v73, v104, v105
	v_add_f32_e32 v75, 0x42000000, v74
	v_exp_f32_e32 v72, v72
	v_exp_f32_e32 v73, v73
	v_fma_f32 v96, v75, v104, v105
	v_add_f32_e32 v75, 0x40400000, v107
	v_mul_f32_e32 v56, v56, v46
	v_mul_f32_e32 v57, v57, v47
	v_add_f32_e32 v46, 0x41000000, v107
	v_add_f32_e32 v94, 0x42000000, v75
	v_add_f32_e32 v47, 0x42000000, v46
	v_fma_f32 v97, v94, v104, v105
	v_add_f32_e32 v94, 0, v107
	v_fma_f32 v47, v47, v104, v105
	v_add_f32_e32 v95, 0x42000000, v94
	v_mul_f32_e32 v38, v38, v72
	v_mul_f32_e32 v39, v39, v73
	v_exp_f32_e32 v72, v47
	v_add_f32_e32 v47, 0x41100000, v107
	v_fma_f32 v100, v95, v104, v105
	v_add_f32_e32 v95, 1.0, v107
	v_add_f32_e32 v65, 0x42000000, v65
	v_add_f32_e32 v67, 0x42000000, v67
	v_add_f32_e32 v73, 0x42000000, v47
	v_add_f32_e32 v101, 0x42000000, v95
	v_fma_f32 v65, v65, v104, v105
	v_fma_f32 v67, v67, v104, v105
	v_fma_f32 v71, v71, v104, v105
	v_fma_f32 v73, v73, v104, v105
	v_fma_f32 v46, v46, v104, v105
	v_fma_f32 v47, v47, v104, v105
	v_fma_f32 v74, v74, v104, v105
	v_fma_f32 v75, v75, v104, v105
	v_fma_f32 v101, v101, v104, v105
	v_fma_f32 v94, v94, v104, v105
	v_fmac_f32_e32 v105, v95, v104
	v_exp_f32_e32 v46, v46
	v_exp_f32_e32 v47, v47
	v_exp_f32_e32 v94, v94
	v_exp_f32_e32 v95, v105
	v_exp_f32_e32 v74, v74
	v_exp_f32_e32 v75, v75
	v_exp_f32_e32 v73, v73
	v_mul_f32_e32 v52, v52, v46
	v_mul_f32_e32 v53, v53, v47
	v_exp_f32_e32 v96, v96
	v_mul_f32_e32 v46, v48, v94
	v_mul_f32_e32 v47, v49, v95
	v_cvt_pk_bf16_f32 v49, v54, v55
	v_exp_f32_e32 v97, v97
	v_exp_f32_e32 v54, v100
	v_exp_f32_e32 v55, v101
	v_exp_f32_e32 v67, v67
	v_exp_f32_e32 v71, v71
	v_mul_f32_e32 v50, v50, v74
	v_mul_f32_e32 v51, v51, v75
	v_cvt_pk_bf16_f32 v46, v46, v47
	v_cvt_pk_bf16_f32 v47, v50, v51
	v_cvt_pk_bf16_f32 v48, v52, v53
	v_mul_f32_e32 v36, v36, v72
	v_mul_f32_e32 v37, v37, v73
	v_mul_f32_e32 v34, v34, v96
	v_mul_f32_e32 v35, v35, v97
	v_mul_f32_e32 v32, v32, v54
	v_mul_f32_e32 v33, v33, v55
	v_mul_f32_e32 v42, v42, v66
	v_mul_f32_e32 v43, v43, v67
	v_cvt_pk_bf16_f32 v32, v32, v33
	v_cvt_pk_bf16_f32 v33, v34, v35
	v_cvt_pk_bf16_f32 v34, v36, v37
	v_mul_f32_e32 v36, v40, v70
	v_mul_f32_e32 v37, v41, v71
	v_cvt_pk_bf16_f32 v50, v56, v57
	v_cvt_pk_bf16_f32 v36, v36, v37
	v_cvt_pk_bf16_f32 v37, v42, v43
	ds_read_b64_tr_b16 v[40:41], v106 offset:16384
	ds_read_b64_tr_b16 v[42:43], v106 offset:16896
	ds_read_b64_tr_b16 v[54:55], v106 offset:17408
	ds_read_b64_tr_b16 v[56:57], v106 offset:17920
	s_waitcnt lgkmcnt(10)
	v_mfma_f32_32x32x16_bf16 v[16:31], v[46:49], v[90:93], v[16:31]
	v_cvt_pk_bf16_f32 v51, v58, v59
	v_cvt_pk_bf16_f32 v52, v60, v61
	v_cvt_pk_bf16_f32 v53, v62, v63
	v_exp_f32_e32 v65, v65
	v_cvt_pk_bf16_f32 v35, v38, v39
	v_mul_f32_e32 v38, v44, v64
	v_mul_f32_e32 v39, v45, v65
	s_waitcnt lgkmcnt(2)
	v_mfma_f32_32x32x16_bf16 v[0:15], v[46:49], v[40:43], v[0:15]
	ds_read_b64_tr_b16 v[40:41], v106 offset:18432
	ds_read_b64_tr_b16 v[42:43], v106 offset:18944
	ds_read_b64_tr_b16 v[44:45], v106 offset:19456
	ds_read_b64_tr_b16 v[46:47], v106 offset:19968
	v_cvt_pk_bf16_f32 v38, v38, v39
	v_cvt_pk_bf16_f32 v39, v68, v69
	v_mfma_f32_32x32x16_bf16 v[16:31], v[50:53], v[82:85], v[16:31]
	s_waitcnt lgkmcnt(4)
	v_mfma_f32_32x32x16_bf16 v[0:15], v[50:53], v[54:57], v[0:15]
	v_mfma_f32_32x32x16_bf16 v[16:31], v[32:35], v[86:89], v[16:31]
	s_waitcnt lgkmcnt(2)
	v_mfma_f32_32x32x16_bf16 v[0:15], v[32:35], v[40:43], v[0:15]
	v_mfma_f32_32x32x16_bf16 v[16:31], v[36:39], v[76:79], v[16:31]
	s_waitcnt lgkmcnt(0)
	v_mfma_f32_32x32x16_bf16 v[0:15], v[36:39], v[44:47], v[0:15]
	s_cbranch_vccnz .LBB0_205
	s_lshl_b32 s0, s2, 3
	s_or_b32 s36, s0, s3
	s_ashr_i32 s37, s36, 31
	s_lshl_b64 s[36:37], s[36:37], 14
	v_readlane_b32 s0, v255, 6
	s_add_u32 s36, s0, s36
	v_readlane_b32 s0, v255, 7
	v_lshlrev_b32_e32 v32, 2, v80
	s_addc_u32 s37, s0, s37
	v_ashrrev_i32_e32 v99, 31, v98
	v_ashrrev_i32_e32 v33, 31, v32
	v_or_b32_e32 v38, 1, v32
	v_lshl_add_u64 v[34:35], v[98:99], 2, s[36:37]
	v_lshlrev_b64 v[36:37], 8, v[32:33]
	v_ashrrev_i32_e32 v39, 31, v38
	v_lshl_add_u64 v[36:37], v[34:35], 0, v[36:37]
	v_lshlrev_b64 v[38:39], 8, v[38:39]
	global_store_dword v[36:37], v16, off
	v_lshl_add_u64 v[38:39], v[34:35], 0, v[38:39]
	v_or_b32_e32 v16, 2, v32
	global_store_dword v[38:39], v17, off
	v_ashrrev_i32_e32 v17, 31, v16
	v_or_b32_e32 v40, 3, v32
	v_lshlrev_b64 v[16:17], 8, v[16:17]
	v_ashrrev_i32_e32 v41, 31, v40
	v_lshl_add_u64 v[16:17], v[34:35], 0, v[16:17]
	v_lshlrev_b64 v[40:41], 8, v[40:41]
	global_store_dword v[16:17], v18, off
	v_lshl_add_u64 v[40:41], v[34:35], 0, v[40:41]
	v_add_u32_e32 v18, 8, v32
	global_store_dword v[40:41], v19, off
	v_ashrrev_i32_e32 v19, 31, v18
	v_add_u32_e32 v42, 9, v32
	v_lshlrev_b64 v[18:19], 8, v[18:19]
	v_ashrrev_i32_e32 v43, 31, v42
	v_lshl_add_u64 v[18:19], v[34:35], 0, v[18:19]
	v_lshlrev_b64 v[42:43], 8, v[42:43]
	global_store_dword v[18:19], v20, off
	v_lshl_add_u64 v[42:43], v[34:35], 0, v[42:43]
	v_add_u32_e32 v20, 10, v32
	global_store_dword v[42:43], v21, off
	v_ashrrev_i32_e32 v21, 31, v20
	v_add_u32_e32 v44, 11, v32
	v_lshlrev_b64 v[20:21], 8, v[20:21]
	v_ashrrev_i32_e32 v45, 31, v44
	v_lshl_add_u64 v[20:21], v[34:35], 0, v[20:21]
	v_lshlrev_b64 v[44:45], 8, v[44:45]
	global_store_dword v[20:21], v22, off
	v_lshl_add_u64 v[44:45], v[34:35], 0, v[44:45]
	v_add_u32_e32 v22, 16, v32
	global_store_dword v[44:45], v23, off
	v_ashrrev_i32_e32 v23, 31, v22
	v_add_u32_e32 v46, 17, v32
	v_lshlrev_b64 v[22:23], 8, v[22:23]
	v_ashrrev_i32_e32 v47, 31, v46
	v_lshl_add_u64 v[22:23], v[34:35], 0, v[22:23]
	v_lshlrev_b64 v[46:47], 8, v[46:47]
	global_store_dword v[22:23], v24, off
	v_lshl_add_u64 v[46:47], v[34:35], 0, v[46:47]
	v_add_u32_e32 v24, 18, v32
	global_store_dword v[46:47], v25, off
	v_ashrrev_i32_e32 v25, 31, v24
	v_add_u32_e32 v48, 19, v32
	v_lshlrev_b64 v[24:25], 8, v[24:25]
	v_ashrrev_i32_e32 v49, 31, v48
	v_lshl_add_u64 v[24:25], v[34:35], 0, v[24:25]
	v_lshlrev_b64 v[48:49], 8, v[48:49]
	global_store_dword v[24:25], v26, off
	v_lshl_add_u64 v[48:49], v[34:35], 0, v[48:49]
	v_add_u32_e32 v26, 24, v32
	global_store_dword v[48:49], v27, off
	v_ashrrev_i32_e32 v27, 31, v26
	v_add_u32_e32 v50, 25, v32
	v_lshlrev_b64 v[26:27], 8, v[26:27]
	v_ashrrev_i32_e32 v51, 31, v50
	v_lshl_add_u64 v[26:27], v[34:35], 0, v[26:27]
	v_lshlrev_b64 v[50:51], 8, v[50:51]
	global_store_dword v[26:27], v28, off
	v_lshl_add_u64 v[50:51], v[34:35], 0, v[50:51]
	v_add_u32_e32 v28, 26, v32
	v_add_u32_e32 v32, 27, v32
	global_store_dword v[50:51], v29, off
	v_ashrrev_i32_e32 v29, 31, v28
	v_ashrrev_i32_e32 v33, 31, v32
	v_lshlrev_b64 v[28:29], 8, v[28:29]
	v_lshlrev_b64 v[32:33], 8, v[32:33]
	v_lshl_add_u64 v[28:29], v[34:35], 0, v[28:29]
	v_lshl_add_u64 v[32:33], v[34:35], 0, v[32:33]
	global_store_dword v[28:29], v30, off
	global_store_dword v[32:33], v31, off
	global_store_dword v[36:37], v0, off offset:128
	global_store_dword v[38:39], v1, off offset:128
	global_store_dword v[16:17], v2, off offset:128
	global_store_dword v[40:41], v3, off offset:128
	global_store_dword v[18:19], v4, off offset:128
	global_store_dword v[42:43], v5, off offset:128
	global_store_dword v[20:21], v6, off offset:128
	global_store_dword v[44:45], v7, off offset:128
	global_store_dword v[22:23], v8, off offset:128
	global_store_dword v[46:47], v9, off offset:128
	global_store_dword v[24:25], v10, off offset:128
	global_store_dword v[48:49], v11, off offset:128
	global_store_dword v[26:27], v12, off offset:128
	global_store_dword v[50:51], v13, off offset:128
	global_store_dword v[28:29], v14, off offset:128
	global_store_dword v[32:33], v15, off offset:128

.LBB0_242:
	s_mul_i32 s37, s60, 0x5000
	s_add_i32 s37, s37, 0
	v_add_u32_e32 v36, s37, v144
	s_waitcnt vmcnt(0)
	s_mov_b64 s[100:101], exec
	s_mov_b64 exec, s[12:13]
	global_load_dword v184, v[174:175], off sc1
	s_mov_b64 exec, s[42:43]
	global_atomic_add v221, v[182:183], v181, off sc0
	s_mov_b64 exec, s[100:101]
	s_barrier
	v_add_u32_e32 v32, v36, v151
	ds_read_b128 v[48:51], v32
	ds_read_b128 v[32:35], v32 offset:4096
	v_add_u32_e32 v37, v36, v145
	ds_read_b128 v[64:67], v37
	ds_read_b128 v[52:55], v37 offset:4096
	v_add_u32_e32 v37, v36, v146
	v_add_u32_e32 v36, v36, v147
	ds_read_b128 v[68:71], v37
	ds_read_b128 v[56:59], v37 offset:4096
	ds_read_b128 v[72:75], v36
	ds_read_b128 v[60:63], v36 offset:4096
	s_waitcnt lgkmcnt(6)
	v_mfma_f32_32x32x16_bf16 v[32:47], v[32:35], v[94:97], 0
	s_lshl_b32 s0, s54, 6
	v_add_u32_e32 v130, s33, v116
	s_mov_b32 s1, 0x800000
	s_mov_b32 s72, 0x40c00000
	s_mov_b64 s[66:67], 0x4000
	v_readlane_b32 s73, v254, 13
	s_waitcnt lgkmcnt(4)
	v_mfma_f32_32x32x16_bf16 v[32:47], v[52:55], v[90:93], v[32:47]
	v_add3_u32 v52, s37, v117, v143
	v_add_u32_e32 v131, v52, v142
	ds_read_b64_tr_b16 v[110:111], v131 offset:12288
	ds_read_b64_tr_b16 v[112:113], v131 offset:12800
	ds_read_b64_tr_b16 v[106:107], v131 offset:13312
	ds_read_b64_tr_b16 v[108:109], v131 offset:13824
	ds_read_b64_tr_b16 v[102:103], v131 offset:14336
	ds_read_b64_tr_b16 v[104:105], v131 offset:14848
	ds_read_b64_tr_b16 v[98:99], v131 offset:15360
	ds_read_b64_tr_b16 v[100:101], v131 offset:15872
	s_add_i32 s37, s0, 0xffffff80
	s_addk_i32 s0, 0xffbf
	s_cmp_ge_u32 s0, s33
	s_cselect_b64 s[58:59], -1, 0
	s_waitcnt lgkmcnt(10)
	v_mfma_f32_32x32x16_bf16 v[32:47], v[56:59], v[86:89], v[32:47]
	s_cmp_lt_u32 s0, s33
	s_cselect_b64 s[54:55], -1, 0
	s_cmp_gt_u32 s37, s50
	s_cselect_b64 s[62:63], -1, 0
	s_or_b64 s[54:55], s[54:55], s[62:63]
	s_mov_b64 s[62:63], -1
	s_and_b64 vcc, exec, s[54:55]
	s_waitcnt lgkmcnt(8)
	v_mfma_f32_32x32x16_bf16 v[32:47], v[60:63], v[82:85], v[32:47]
	v_mfma_f32_32x32x16_bf16 v[48:63], v[48:51], v[94:97], 0
	v_mfma_f32_32x32x16_bf16 v[48:63], v[64:67], v[90:93], v[48:63]
	v_mfma_f32_32x32x16_bf16 v[48:63], v[68:71], v[86:89], v[48:63]
	v_mfma_f32_32x32x16_bf16 v[48:63], v[72:75], v[82:85], v[48:63]
	s_cbranch_vccnz .LBB0_244
	v_add_u32_e32 v64, s37, v141
	v_sub_u32_e32 v64, v130, v64
	v_cvt_f32_i32_e32 v64, v64
	s_mov_b32 s0, 0xc2000000
	v_cmp_lt_f32_e32 vcc, 0, v64
	v_add_f32_e32 v65, -1.0, v64
	s_mov_b32 s54, -2.0
	v_cndmask_b32_e32 v66, v137, v115, vcc
	v_mul_f32_e64 v66, |v64|, v66
	v_cmp_lt_f32_e32 vcc, 0, v65
	v_exp_f32_e32 v133, v66
	s_mov_b32 s55, 0xc0400000
	v_cndmask_b32_e32 v66, v137, v115, vcc
	v_mul_f32_e64 v66, |v65|, v66
	v_exp_f32_e32 v134, v66
	v_add_f32_e32 v66, s0, v64
	v_add_f32_e32 v67, s0, v65
	s_mov_b64 s[62:63], 0
	v_cmp_lt_f32_e32 vcc, 0, v66
	s_nop 1
	v_cndmask_b32_e32 v68, v137, v115, vcc
	v_cmp_lt_f32_e32 vcc, 0, v67
	v_mul_f32_e64 v68, |v66|, v68
	v_exp_f32_e32 v68, v68
	v_cndmask_b32_e32 v69, v137, v115, vcc
	v_mul_f32_e64 v69, |v67|, v69
	v_exp_f32_e32 v69, v69
	v_cmp_neq_f32_e32 vcc, 0, v67
	s_nop 1
	v_cndmask_b32_e32 v67, 2.0, v69, vcc
	v_cmp_neq_f32_e32 vcc, 0, v66
	s_nop 1
	v_cndmask_b32_e32 v66, 2.0, v68, vcc
	v_mul_f32_e32 v116, v32, v66
	v_mul_f32_e32 v117, v33, v67
	v_add_f32_e32 v66, s54, v64
	v_add_f32_e32 v67, s55, v64
	v_cmp_lt_f32_e32 vcc, 0, v66
	s_mov_b32 s54, 0xc1000000
	s_mov_b32 s55, 0xc1100000
	v_cndmask_b32_e32 v68, v137, v115, vcc
	v_mul_f32_e64 v68, |v66|, v68
	v_cmp_lt_f32_e32 vcc, 0, v67
	v_exp_f32_e32 v135, v68
	s_nop 0
	v_cndmask_b32_e32 v68, v137, v115, vcc
	v_mul_f32_e64 v68, |v67|, v68
	v_exp_f32_e32 v141, v68
	v_add_f32_e32 v68, s0, v66
	v_add_f32_e32 v69, s0, v67
	s_nop 0
	v_cmp_lt_f32_e32 vcc, 0, v68
	s_nop 1
	v_cndmask_b32_e32 v70, v137, v115, vcc
	v_cmp_lt_f32_e32 vcc, 0, v69
	v_mul_f32_e64 v70, |v68|, v70
	v_exp_f32_e32 v70, v70
	v_cndmask_b32_e32 v71, v137, v115, vcc
	v_mul_f32_e64 v71, |v69|, v71
	v_exp_f32_e32 v71, v71
	v_cmp_neq_f32_e32 vcc, 0, v69
	s_nop 1
	v_cndmask_b32_e32 v69, 2.0, v71, vcc
	v_cmp_neq_f32_e32 vcc, 0, v68
	s_nop 1
	v_cndmask_b32_e32 v68, 2.0, v70, vcc
	v_mul_f32_e32 v118, v34, v68
	v_mul_f32_e32 v119, v35, v69
	v_add_f32_e32 v68, s54, v64
	v_add_f32_e32 v69, s55, v64
	v_cmp_lt_f32_e32 vcc, 0, v68
	s_mov_b32 s54, 0xc1200000
	s_mov_b32 s55, 0xc1300000
	v_cndmask_b32_e32 v70, v137, v115, vcc
	v_mul_f32_e64 v70, |v68|, v70
	v_cmp_lt_f32_e32 vcc, 0, v69
	v_exp_f32_e32 v142, v70
	s_nop 0
	v_cndmask_b32_e32 v70, v137, v115, vcc
	v_mul_f32_e64 v70, |v69|, v70
	v_exp_f32_e32 v143, v70
	v_add_f32_e32 v70, s0, v68
	v_add_f32_e32 v71, s0, v69
	s_nop 0
	v_cmp_lt_f32_e32 vcc, 0, v70
	s_nop 1
	v_cndmask_b32_e32 v72, v137, v115, vcc
	v_cmp_lt_f32_e32 vcc, 0, v71
	v_mul_f32_e64 v72, |v70|, v72
	v_exp_f32_e32 v72, v72
	v_cndmask_b32_e32 v73, v137, v115, vcc
	v_mul_f32_e64 v73, |v71|, v73
	v_exp_f32_e32 v73, v73
	v_cmp_neq_f32_e32 vcc, 0, v71
	s_nop 1
	v_cndmask_b32_e32 v71, 2.0, v73, vcc
	v_cmp_neq_f32_e32 vcc, 0, v70
	s_nop 1
	v_cndmask_b32_e32 v70, 2.0, v72, vcc
	v_mul_f32_e32 v120, v36, v70
	v_mul_f32_e32 v121, v37, v71
	v_add_f32_e32 v70, s54, v64
	v_add_f32_e32 v71, s55, v64
	v_cmp_lt_f32_e32 vcc, 0, v70
	s_mov_b32 s54, 0xc1800000
	s_mov_b32 s55, 0xc1880000
	v_cndmask_b32_e32 v72, v137, v115, vcc
	v_mul_f32_e64 v72, |v70|, v72
	v_cmp_lt_f32_e32 vcc, 0, v71
	v_exp_f32_e32 v144, v72
	s_nop 0
	v_cndmask_b32_e32 v72, v137, v115, vcc
	v_mul_f32_e64 v72, |v71|, v72
	v_exp_f32_e32 v145, v72
	v_add_f32_e32 v72, s0, v70
	v_add_f32_e32 v73, s0, v71
	s_nop 0
	v_cmp_lt_f32_e32 vcc, 0, v72
	s_nop 1
	v_cndmask_b32_e32 v74, v137, v115, vcc
	v_cmp_lt_f32_e32 vcc, 0, v73
	v_mul_f32_e64 v74, |v72|, v74
	v_exp_f32_e32 v74, v74
	v_cndmask_b32_e32 v75, v137, v115, vcc
	v_mul_f32_e64 v75, |v73|, v75
	v_exp_f32_e32 v75, v75
	v_cmp_neq_f32_e32 vcc, 0, v73
	s_nop 1
	v_cndmask_b32_e32 v73, 2.0, v75, vcc
	v_cmp_neq_f32_e32 vcc, 0, v72
	s_nop 1
	v_cndmask_b32_e32 v72, 2.0, v74, vcc
	v_mul_f32_e32 v122, v38, v72
	v_mul_f32_e32 v123, v39, v73
	v_add_f32_e32 v72, s54, v64
	v_add_f32_e32 v73, s55, v64
	v_cmp_lt_f32_e32 vcc, 0, v72
	s_mov_b32 s54, 0xc1900000
	s_mov_b32 s55, 0xc1980000
	v_cndmask_b32_e32 v74, v137, v115, vcc
	v_mul_f32_e64 v74, |v72|, v74
	v_cmp_lt_f32_e32 vcc, 0, v73
	v_exp_f32_e32 v146, v74
	s_nop 0
	v_cndmask_b32_e32 v74, v137, v115, vcc
	v_mul_f32_e64 v74, |v73|, v74
	v_exp_f32_e32 v147, v74
	v_add_f32_e32 v74, s0, v72
	v_add_f32_e32 v75, s0, v73
	s_nop 0
	v_cmp_lt_f32_e32 vcc, 0, v74
	s_nop 1
	v_cndmask_b32_e32 v76, v137, v115, vcc
	v_cmp_lt_f32_e32 vcc, 0, v75
	v_mul_f32_e64 v76, |v74|, v76
	v_exp_f32_e32 v76, v76
	v_cndmask_b32_e32 v77, v137, v115, vcc
	v_mul_f32_e64 v77, |v75|, v77
	v_exp_f32_e32 v77, v77
	v_cmp_neq_f32_e32 vcc, 0, v75
	s_nop 1
	v_cndmask_b32_e32 v75, 2.0, v77, vcc
	v_cmp_neq_f32_e32 vcc, 0, v74
	s_nop 1
	v_cndmask_b32_e32 v74, 2.0, v76, vcc
	v_mul_f32_e32 v124, v40, v74
	v_mul_f32_e32 v125, v41, v75
	v_add_f32_e32 v74, s54, v64
	v_add_f32_e32 v75, s55, v64
	v_cmp_lt_f32_e32 vcc, 0, v74
	s_mov_b32 s54, 0xc1c00000
	s_mov_b32 s55, 0xc1c80000
	v_cndmask_b32_e32 v76, v137, v115, vcc
	v_mul_f32_e64 v76, |v74|, v76
	v_cmp_lt_f32_e32 vcc, 0, v75
	v_exp_f32_e32 v151, v76
	s_nop 0
	v_cndmask_b32_e32 v76, v137, v115, vcc
	v_mul_f32_e64 v76, |v75|, v76
	v_exp_f32_e32 v152, v76
	v_add_f32_e32 v76, s0, v74
	v_add_f32_e32 v77, s0, v75
	s_nop 0
	v_cmp_lt_f32_e32 vcc, 0, v76
	s_nop 1
	v_cndmask_b32_e32 v78, v137, v115, vcc
	v_cmp_lt_f32_e32 vcc, 0, v77
	v_mul_f32_e64 v78, |v76|, v78
	v_exp_f32_e32 v78, v78
	v_cndmask_b32_e32 v79, v137, v115, vcc
	v_mul_f32_e64 v79, |v77|, v79
	v_exp_f32_e32 v79, v79
	v_cmp_neq_f32_e32 vcc, 0, v77
	s_nop 1
	v_cndmask_b32_e32 v77, 2.0, v79, vcc
	v_cmp_neq_f32_e32 vcc, 0, v76
	s_nop 1
	v_cndmask_b32_e32 v76, 2.0, v78, vcc
	v_mul_f32_e32 v126, v42, v76
	v_mul_f32_e32 v127, v43, v77
	v_add_f32_e32 v76, s54, v64
	v_add_f32_e32 v77, s55, v64
	v_cmp_lt_f32_e32 vcc, 0, v76
	s_mov_b32 s54, 0xc1d00000
	s_mov_b32 s55, 0xc1d80000
	v_cndmask_b32_e32 v78, v137, v115, vcc
	v_mul_f32_e64 v78, |v76|, v78
	v_cmp_lt_f32_e32 vcc, 0, v77
	v_exp_f32_e32 v153, v78
	s_nop 0
	v_cndmask_b32_e32 v78, v137, v115, vcc
	v_mul_f32_e64 v78, |v77|, v78
	v_exp_f32_e32 v154, v78
	v_add_f32_e32 v78, s0, v76
	v_add_f32_e32 v79, s0, v77
	s_nop 0
	v_cmp_lt_f32_e32 vcc, 0, v78
	s_nop 1
	v_cndmask_b32_e32 v128, v137, v115, vcc
	v_cmp_lt_f32_e32 vcc, 0, v79
	v_mul_f32_e64 v128, |v78|, v128
	v_exp_f32_e32 v128, v128
	v_cndmask_b32_e32 v129, v137, v115, vcc
	v_mul_f32_e64 v129, |v79|, v129
	v_exp_f32_e32 v129, v129
	v_cmp_neq_f32_e32 vcc, 0, v79
	s_nop 1
	v_cndmask_b32_e32 v79, 2.0, v129, vcc
	v_cmp_neq_f32_e32 vcc, 0, v78
	s_nop 1
	v_cndmask_b32_e32 v78, 2.0, v128, vcc
	v_mul_f32_e32 v128, v44, v78
	v_mul_f32_e32 v129, v45, v79
	v_add_f32_e32 v78, s54, v64
	v_add_f32_e32 v79, s55, v64
	v_add_f32_e32 v132, 0xc2000000, v78
	v_cmp_lt_f32_e32 vcc, 0, v78
	s_nop 1
	v_cndmask_b32_e32 v155, v137, v115, vcc
	v_cmp_lt_f32_e32 vcc, 0, v132
	v_mul_f32_e64 v155, |v78|, v155
	v_exp_f32_e32 v155, v155
	v_cndmask_b32_e32 v156, v137, v115, vcc
	v_mul_f32_e64 v156, |v132|, v156
	v_exp_f32_e32 v156, v156
	v_cmp_lt_f32_e32 vcc, 0, v79
	s_nop 1
	v_cndmask_b32_e32 v157, v137, v115, vcc
	v_mul_f32_e64 v157, |v79|, v157
	v_exp_f32_e32 v157, v157
	v_cmp_neq_f32_e32 vcc, 0, v132
	s_nop 1
	v_cndmask_b32_e32 v132, 2.0, v156, vcc
	v_add_f32_e32 v156, 0xc2000000, v79
	v_cmp_lt_f32_e32 vcc, 0, v156
	v_mul_f32_e32 v132, v46, v132
	s_nop 0
	v_cndmask_b32_e32 v158, v137, v115, vcc
	v_cmp_neq_f32_e32 vcc, 0, v79
	v_mul_f32_e64 v158, |v156|, v158
	v_exp_f32_e32 v158, v158
	v_cndmask_b32_e32 v79, 2.0, v157, vcc
	v_cmp_neq_f32_e32 vcc, 0, v78
	s_nop 1
	v_cndmask_b32_e32 v78, 2.0, v155, vcc
	v_cmp_neq_f32_e32 vcc, 0, v77
	s_nop 1
	v_cndmask_b32_e32 v77, 2.0, v154, vcc
	v_cmp_neq_f32_e32 vcc, 0, v76
	s_nop 1
	v_cndmask_b32_e32 v76, 2.0, v153, vcc
	v_cmp_neq_f32_e32 vcc, 0, v75
	s_nop 1
	v_cndmask_b32_e32 v75, 2.0, v152, vcc
	v_cmp_neq_f32_e32 vcc, 0, v74
	s_nop 1
	v_cndmask_b32_e32 v74, 2.0, v151, vcc
	v_cmp_neq_f32_e32 vcc, 0, v73
	s_nop 1
	v_cndmask_b32_e32 v73, 2.0, v147, vcc
	v_cmp_neq_f32_e32 vcc, 0, v72
	s_nop 1
	v_cndmask_b32_e32 v72, 2.0, v146, vcc
	v_cmp_neq_f32_e32 vcc, 0, v71
	s_nop 1
	v_cndmask_b32_e32 v71, 2.0, v145, vcc
	v_cmp_neq_f32_e32 vcc, 0, v70
	s_nop 1
	v_cndmask_b32_e32 v70, 2.0, v144, vcc
	v_cmp_neq_f32_e32 vcc, 0, v69
	s_nop 1
	v_cndmask_b32_e32 v69, 2.0, v143, vcc
	v_cmp_neq_f32_e32 vcc, 0, v68
	s_nop 1
	v_cndmask_b32_e32 v68, 2.0, v142, vcc
	v_cmp_neq_f32_e32 vcc, 0, v67
	s_nop 1
	v_cndmask_b32_e32 v67, 2.0, v141, vcc
	v_cmp_neq_f32_e32 vcc, 0, v66
	s_nop 1
	v_cndmask_b32_e32 v66, 2.0, v135, vcc
	v_cmp_neq_f32_e32 vcc, 0, v64
	s_nop 1
	v_cndmask_b32_e32 v64, 2.0, v133, vcc
	v_cmp_neq_f32_e32 vcc, 0, v65
	s_nop 1
	v_cndmask_b32_e32 v65, 2.0, v134, vcc
	v_cmp_neq_f32_e32 vcc, 0, v156
	s_nop 1
	v_cndmask_b32_e32 v133, 2.0, v158, vcc

.LBB0_323:
	s_andn2_b64 vcc, exec, s[12:13]
	s_cbranch_vccnz .LBB0_340
	s_lshl_b32 s0, s0, 2
	v_readlane_b32 s1, v254, 12
	s_add_i32 s40, s0, s1
	s_ashr_i32 s41, s40, 31
	s_lshl_b64 s[40:41], s[40:41], 2
	v_readlane_b32 s0, v255, 15
	s_add_u32 s0, s0, s40
	v_readlane_b32 s1, v255, 16
	s_addc_u32 s33, s1, s41
	s_ashr_i32 s37, s58, 8
	s_add_i32 s37, s37, s79
	s_lshl_b32 s40, s37, 2
	s_ashr_i32 s41, s40, 31
	s_lshl_b64 s[40:41], s[40:41], 2
	v_readlane_b32 s1, v255, 17
	v_mov_b32_e32 v4, v205
	s_add_u32 s40, s1, s40
	v_readlane_b32 s1, v255, 18
	s_addc_u32 s41, s1, s41
	v_lshlrev_b32_e32 v0, 2, v4
	v_ashrrev_i32_e32 v1, 31, v0
	v_cmp_eq_u32_e32 vcc, s11, v4
	v_lshl_add_u64 v[0:1], v[0:1], 2, s[40:41]
	v_mov_b32_e32 v2, s33
	s_and_b64 vcc, s[28:29], vcc
	v_cndmask_b32_e32 v1, v1, v2, vcc
	v_mov_b32_e32 v2, s0
	v_add_u32_e32 v3, s11, v3
	v_cndmask_b32_e32 v0, v0, v2, vcc
	v_cndmask_b32_e64 v2, 19, 12, vcc
	v_cmp_lt_i32_e64 s[40:41], v4, v3
	s_mov_b32 s0, 1
	s_mov_b64 s[62:63], 0
	s_branch .LBB0_327

.LBB0_354:
	s_or_b64 exec, exec, s[28:29]
	s_andn2_b64 vcc, exec, s[12:13]
	s_cbranch_vccnz .Lmz_done
	s_ashr_i32 s100, s5, 8
	s_add_i32 s100, s100, s79
	s_lshl_b32 s100, s100, 4
	v_readlane_b32 s101, v255, 10
	s_add_u32 s100, s101, s100
	v_readlane_b32 s101, v255, 11
	s_addc_u32 s101, s101, 0
	v_mov_b32_e32 v176, s100
	v_mov_b32_e32 v177, s101
	s_movk_i32 s100, 0
.Lmz_spin:
	global_load_dword v173, v[176:177], off sc1
	s_waitcnt vmcnt(0)
	v_readfirstlane_b32 s101, v173
	s_cmp_gt_u32 s101, 3
	s_cbranch_scc1 .Lmz_done
	s_add_i32 s100, s100, 1
	s_cmp_gt_u32 s100, 0xffff
	s_cbranch_scc1 .Lmz_done
	s_sleep 1
	s_branch .Lmz_spin
.Lmz_done:
	s_ashr_i32 s0, s5, 8
	s_add_i32 s0, s0, s79
	s_lshl_b32 s28, s0, 2
	s_ashr_i32 s29, s28, 31
	s_lshl_b64 s[28:29], s[28:29], 2
	s_add_u32 s64, s39, s28
	s_addc_u32 s65, s8, s29
	s_lshl_b32 s0, s2, 6
	s_add_i32 s60, s0, 0x280
	v_ashrrev_i32_e32 v56, 3, v80
	s_add_i32 s5, s5, s51
	s_lshl_b64 s[28:29], s[60:61], 1
	v_lshlrev_b32_e32 v17, 3, v80
	s_waitcnt lgkmcnt(0)
	v_add_u32_e32 v16, s5, v56
	s_add_u32 s2, s18, s28
	v_and_b32_e32 v57, 56, v17
	s_addc_u32 s3, s19, s29
	v_lshlrev_b32_e32 v80, 1, v57
	v_ashrrev_i32_e32 v17, 31, v16
	v_lshl_add_u64 v[18:19], s[2:3], 0, v[80:81]
	v_lshlrev_b64 v[54:55], 11, v[16:17]
	v_lshl_add_u64 v[20:21], v[18:19], 0, v[54:55]
	s_barrier
	global_load_dwordx4 v[28:31], v[20:21], off
	v_add_u32_e32 v20, 8, v16
	v_ashrrev_i32_e32 v21, 31, v20
	v_lshlrev_b64 v[52:53], 11, v[20:21]
	v_lshl_add_u64 v[20:21], v[18:19], 0, v[52:53]
	global_load_dwordx4 v[24:27], v[20:21], off
	v_add_u32_e32 v20, 16, v16
	v_ashrrev_i32_e32 v21, 31, v20
	v_lshlrev_b64 v[50:51], 11, v[20:21]
	v_lshl_add_u64 v[20:21], v[18:19], 0, v[50:51]
	global_load_dwordx4 v[20:23], v[20:21], off
	v_add_u32_e32 v16, 24, v16
	v_ashrrev_i32_e32 v17, 31, v16
	v_lshlrev_b64 v[48:49], 11, v[16:17]
	v_lshl_add_u64 v[16:17], v[18:19], 0, v[48:49]
	global_load_dwordx4 v[16:19], v[16:17], off
	s_movk_i32 s0, 0x440
	v_lshlrev_b32_e32 v58, 2, v131
	v_mul_lo_u32 v59, v130, s0
	v_add3_u32 v58, s9, v58, v59
	ds_write2_b32 v58, v0, v32 offset1:32
	ds_write2_b32 v58, v1, v33 offset0:68 offset1:100
	ds_write2_b32 v58, v2, v34 offset0:136 offset1:168
	ds_write2_b32 v58, v3, v35 offset0:204 offset1:236
	v_add_u32_e32 v0, 0x800, v58
	ds_write2_b32 v0, v4, v36 offset0:32 offset1:64
	ds_write2_b32 v0, v5, v37 offset0:100 offset1:132
	ds_write2_b32 v0, v6, v38 offset0:168 offset1:200
	v_add_u32_e32 v0, 0xa00, v58
	ds_write2_b32 v0, v7, v39 offset0:108 offset1:140
	v_add_u32_e32 v0, 0x1000, v58
	ds_write2_b32 v0, v8, v40 offset0:64 offset1:96
	ds_write2_b32 v0, v9, v41 offset0:132 offset1:164
	ds_write2_b32 v0, v10, v42 offset0:200 offset1:232
	v_add_u32_e32 v0, 0x1400, v58
	ds_write2_b32 v0, v11, v43 offset0:12 offset1:44
	v_add_u32_e32 v0, 0x1800, v58
	ds_write2_b32 v0, v12, v44 offset0:96 offset1:128
	ds_write2_b32 v0, v13, v45 offset0:164 offset1:196
	v_add_u32_e32 v0, 0x1a00, v58
	ds_write2_b32 v0, v14, v46 offset0:104 offset1:136
	v_add_u32_e32 v0, 0x1c00, v58
	ds_write2_b32 v0, v15, v47 offset0:44 offset1:76
	v_lshlrev_b32_e32 v0, 2, v57
	v_mul_lo_u32 v1, v56, s77
	v_add3_u32 v9, s9, v0, v1
	v_lshl_add_u32 v12, v56, 2, s6
	s_waitcnt lgkmcnt(0)
	ds_read_b128 v[0:3], v9
	ds_read_b128 v[4:7], v9 offset:16
	ds_read_b32 v8, v12
	s_mov_b64 s[40:41], s[42:43]
	s_waitcnt lgkmcnt(0)
	v_pk_mul_f32 v[0:1], v[0:1], v[8:9] op_sel_hi:[1,0]
	v_pk_mul_f32 v[2:3], v[2:3], v[8:9] op_sel_hi:[1,0]
	s_waitcnt vmcnt(0)
	v_lshlrev_b32_e32 v10, 16, v28
	v_and_b32_e32 v11, 0xffff0000, v28
	v_pk_mul_f32 v[0:1], v[0:1], v[10:11]
	v_lshlrev_b32_e32 v10, 16, v29
	v_and_b32_e32 v11, 0xffff0000, v29
	v_pk_mul_f32 v[2:3], v[2:3], v[10:11]
	v_cvt_pk_bf16_f32 v0, v0, v1
	v_cvt_pk_bf16_f32 v1, v2, v3
	v_pk_mul_f32 v[2:3], v[4:5], v[8:9] op_sel_hi:[1,0]
	v_lshlrev_b32_e32 v4, 16, v30
	v_and_b32_e32 v5, 0xffff0000, v30
	v_pk_mul_f32 v[2:3], v[2:3], v[4:5]
	v_pk_mul_f32 v[4:5], v[6:7], v[8:9] op_sel_hi:[1,0]
	v_lshlrev_b32_e32 v6, 16, v31
	v_and_b32_e32 v7, 0xffff0000, v31
	v_pk_mul_f32 v[4:5], v[4:5], v[6:7]
	v_cvt_pk_bf16_f32 v2, v2, v3
	v_cvt_pk_bf16_f32 v3, v4, v5
	v_lshl_add_u64 v[4:5], s[26:27], 0, v[54:55]
	v_lshl_add_u64 v[4:5], v[4:5], 0, s[28:29]
	v_lshl_add_u64 v[4:5], v[4:5], 0, v[80:81]
	global_store_dwordx4 v[4:5], v[0:3], off sc1
	s_nop 1
	ds_read_b128 v[0:3], v9 offset:2176
	ds_read_b128 v[4:7], v9 offset:2192
	ds_read_b32 v8, v12 offset:32
	v_lshlrev_b32_e32 v10, 16, v24
	v_and_b32_e32 v11, 0xffff0000, v24
	s_waitcnt lgkmcnt(0)
	v_pk_mul_f32 v[0:1], v[0:1], v[8:9] op_sel_hi:[1,0]
	s_nop 0
	v_pk_mul_f32 v[0:1], v[0:1], v[10:11]
	v_pk_mul_f32 v[2:3], v[2:3], v[8:9] op_sel_hi:[1,0]
	v_lshlrev_b32_e32 v10, 16, v25
	v_and_b32_e32 v11, 0xffff0000, v25
	v_pk_mul_f32 v[2:3], v[2:3], v[10:11]
	v_cvt_pk_bf16_f32 v0, v0, v1
	v_cvt_pk_bf16_f32 v1, v2, v3
	v_pk_mul_f32 v[2:3], v[4:5], v[8:9] op_sel_hi:[1,0]
	v_lshlrev_b32_e32 v4, 16, v26
	v_and_b32_e32 v5, 0xffff0000, v26
	v_pk_mul_f32 v[2:3], v[2:3], v[4:5]
	v_pk_mul_f32 v[4:5], v[6:7], v[8:9] op_sel_hi:[1,0]
	v_lshlrev_b32_e32 v6, 16, v27
	v_and_b32_e32 v7, 0xffff0000, v27
	v_pk_mul_f32 v[4:5], v[4:5], v[6:7]
	v_cvt_pk_bf16_f32 v2, v2, v3
	v_cvt_pk_bf16_f32 v3, v4, v5
	v_lshl_add_u64 v[4:5], s[26:27], 0, v[52:53]
	v_lshl_add_u64 v[4:5], v[4:5], 0, s[28:29]
	v_lshl_add_u64 v[4:5], v[4:5], 0, v[80:81]
	global_store_dwordx4 v[4:5], v[0:3], off sc1
	s_nop 1
	ds_read_b128 v[0:3], v9 offset:4352
	ds_read_b128 v[4:7], v9 offset:4368
	ds_read_b32 v8, v12 offset:64
	v_lshlrev_b32_e32 v10, 16, v20
	v_and_b32_e32 v11, 0xffff0000, v20
	s_waitcnt lgkmcnt(0)
	v_pk_mul_f32 v[0:1], v[0:1], v[8:9] op_sel_hi:[1,0]
	s_nop 0
	v_pk_mul_f32 v[0:1], v[0:1], v[10:11]
	v_pk_mul_f32 v[2:3], v[2:3], v[8:9] op_sel_hi:[1,0]
	v_lshlrev_b32_e32 v10, 16, v21
	v_and_b32_e32 v11, 0xffff0000, v21
	v_pk_mul_f32 v[2:3], v[2:3], v[10:11]
	v_cvt_pk_bf16_f32 v0, v0, v1
	v_cvt_pk_bf16_f32 v1, v2, v3
	v_pk_mul_f32 v[2:3], v[4:5], v[8:9] op_sel_hi:[1,0]
	v_lshlrev_b32_e32 v4, 16, v22
	v_and_b32_e32 v5, 0xffff0000, v22
	v_pk_mul_f32 v[2:3], v[2:3], v[4:5]
	v_pk_mul_f32 v[4:5], v[6:7], v[8:9] op_sel_hi:[1,0]
	v_lshlrev_b32_e32 v6, 16, v23
	v_and_b32_e32 v7, 0xffff0000, v23
	v_pk_mul_f32 v[4:5], v[4:5], v[6:7]
	v_cvt_pk_bf16_f32 v2, v2, v3
	v_cvt_pk_bf16_f32 v3, v4, v5
	v_lshl_add_u64 v[4:5], s[26:27], 0, v[50:51]
	v_lshl_add_u64 v[4:5], v[4:5], 0, s[28:29]
	v_lshl_add_u64 v[4:5], v[4:5], 0, v[80:81]
	global_store_dwordx4 v[4:5], v[0:3], off sc1
	s_nop 1
	ds_read_b128 v[0:3], v9 offset:6528
	ds_read_b128 v[4:7], v9 offset:6544
	ds_read_b32 v8, v12 offset:96
	v_lshlrev_b32_e32 v10, 16, v16
	v_and_b32_e32 v11, 0xffff0000, v16
	s_waitcnt lgkmcnt(0)
	v_pk_mul_f32 v[0:1], v[0:1], v[8:9] op_sel_hi:[1,0]
	s_nop 0
	v_pk_mul_f32 v[0:1], v[0:1], v[10:11]
	v_pk_mul_f32 v[2:3], v[2:3], v[8:9] op_sel_hi:[1,0]
	v_lshlrev_b32_e32 v10, 16, v17
	v_and_b32_e32 v11, 0xffff0000, v17
	v_pk_mul_f32 v[2:3], v[2:3], v[10:11]
	v_cvt_pk_bf16_f32 v0, v0, v1
	v_cvt_pk_bf16_f32 v1, v2, v3
	v_pk_mul_f32 v[2:3], v[4:5], v[8:9] op_sel_hi:[1,0]
	v_lshlrev_b32_e32 v4, 16, v18
	v_and_b32_e32 v5, 0xffff0000, v18
	v_pk_mul_f32 v[2:3], v[2:3], v[4:5]
	v_pk_mul_f32 v[4:5], v[6:7], v[8:9] op_sel_hi:[1,0]
	v_lshlrev_b32_e32 v6, 16, v19
	v_and_b32_e32 v7, 0xffff0000, v19
	v_pk_mul_f32 v[4:5], v[4:5], v[6:7]
	v_cvt_pk_bf16_f32 v2, v2, v3
	v_cvt_pk_bf16_f32 v3, v4, v5
	v_lshl_add_u64 v[4:5], s[26:27], 0, v[48:49]
	v_lshl_add_u64 v[4:5], v[4:5], 0, s[28:29]
	v_lshl_add_u64 v[4:5], v[4:5], 0, v[80:81]
	global_store_dwordx4 v[4:5], v[0:3], off sc1
	s_nop 1
	s_waitcnt vmcnt(0)
	s_barrier

.LBB0_1217:
	s_or_b64 exec, exec, s[16:17]
	s_branch .LBB0_481
